# v48 + attention canonicalizing v_max removed (pads re-derived) + FFN1-in tile-header vmcnt(0) drain removed (in-loop counted waits cover it)
# speedup vs baseline: 1.0054x; 1.0054x over previous
.LBB0_247:
	s_ashr_i32 s45, s44, 31
	s_lshl_b64 s[20:21], s[44:45], 19
	s_add_u32 s50, s16, s20
	s_addc_u32 s51, s17, s21
	s_and_b64 s[20:21], s[48:49], exec
	s_cselect_b32 s33, s51, s55
	s_cselect_b32 s39, s50, s54
	s_ashr_i32 s47, s46, 31
	s_lshl_b64 s[20:21], s[46:47], 19
	v_readlane_b32 s26, v255, 29
	v_readlane_b32 s27, v255, 30
	s_add_u32 s52, s26, s20
	s_addc_u32 s53, s27, s21
	s_and_b64 s[20:21], s[48:49], exec
	s_cselect_b32 s45, s53, s57
	s_cselect_b32 s47, s52, s56
	s_add_u32 s54, s54, 0x40080
	s_addc_u32 s55, s55, 0
	s_add_u32 s66, s56, 0x100
	v_mov_b32_e32 v0, 0
	s_addc_u32 s67, s57, 0
	s_mov_b32 s68, -2
	v_mov_b32_e32 v1, v0
	v_mov_b32_e32 v2, v0
	v_mov_b32_e32 v3, v0
	v_mov_b32_e32 v4, v0
	v_mov_b32_e32 v5, v0
	v_mov_b32_e32 v6, v0
	v_mov_b32_e32 v7, v0
	v_mov_b32_e32 v16, v0
	v_mov_b32_e32 v17, v0
	v_mov_b32_e32 v18, v0
	v_mov_b32_e32 v19, v0
	v_mov_b32_e32 v20, v0
	v_mov_b32_e32 v21, v0
	v_mov_b32_e32 v22, v0
	v_mov_b32_e32 v23, v0
	v_mov_b32_e32 v32, v0
	v_mov_b32_e32 v33, v0
	v_mov_b32_e32 v34, v0
	v_mov_b32_e32 v35, v0
	v_mov_b32_e32 v36, v0
	v_mov_b32_e32 v37, v0
	v_mov_b32_e32 v38, v0
	v_mov_b32_e32 v39, v0
	v_mov_b32_e32 v50, v0
	v_mov_b32_e32 v51, v0
	v_mov_b32_e32 v52, v0
	v_mov_b32_e32 v53, v0
	v_mov_b32_e32 v54, v0
	v_mov_b32_e32 v55, v0
	v_mov_b32_e32 v56, v0
	v_mov_b32_e32 v57, v0
	v_mov_b32_e32 v8, v0
	v_mov_b32_e32 v9, v0
	v_mov_b32_e32 v10, v0
	v_mov_b32_e32 v11, v0
	v_mov_b32_e32 v12, v0
	v_mov_b32_e32 v13, v0
	v_mov_b32_e32 v14, v0
	v_mov_b32_e32 v15, v0
	v_mov_b32_e32 v24, v0
	v_mov_b32_e32 v25, v0
	v_mov_b32_e32 v26, v0
	v_mov_b32_e32 v27, v0
	v_mov_b32_e32 v28, v0
	v_mov_b32_e32 v29, v0
	v_mov_b32_e32 v30, v0
	v_mov_b32_e32 v31, v0
	v_mov_b32_e32 v40, v0
	v_mov_b32_e32 v41, v0
	v_mov_b32_e32 v42, v0
	v_mov_b32_e32 v43, v0
	v_mov_b32_e32 v44, v0
	v_mov_b32_e32 v45, v0
	v_mov_b32_e32 v46, v0
	v_mov_b32_e32 v47, v0
	v_mov_b32_e32 v58, v0
	v_mov_b32_e32 v59, v0
	v_mov_b32_e32 v60, v0
	v_mov_b32_e32 v61, v0
	v_mov_b32_e32 v62, v0
	v_mov_b32_e32 v63, v0
	v_mov_b32_e32 v64, v0
	v_mov_b32_e32 v65, v0
	v_mov_b32_e32 v66, v0
	v_mov_b32_e32 v67, v0
	v_mov_b32_e32 v68, v0
	v_mov_b32_e32 v69, v0
	v_mov_b32_e32 v70, v0
	v_mov_b32_e32 v71, v0
	v_mov_b32_e32 v72, v0
	v_mov_b32_e32 v73, v0
	v_mov_b32_e32 v82, v0
	v_mov_b32_e32 v83, v0
	v_mov_b32_e32 v84, v0
	v_mov_b32_e32 v85, v0
	v_mov_b32_e32 v86, v0
	v_mov_b32_e32 v87, v0
	v_mov_b32_e32 v88, v0
	v_mov_b32_e32 v89, v0
	v_mov_b32_e32 v98, v0
	v_mov_b32_e32 v99, v0
	v_mov_b32_e32 v100, v0
	v_mov_b32_e32 v101, v0
	v_mov_b32_e32 v102, v0
	v_mov_b32_e32 v103, v0
	v_mov_b32_e32 v104, v0
	v_mov_b32_e32 v105, v0
	v_mov_b32_e32 v114, v0
	v_mov_b32_e32 v115, v0
	v_mov_b32_e32 v116, v0
	v_mov_b32_e32 v117, v0
	v_mov_b32_e32 v118, v0
	v_mov_b32_e32 v119, v0
	v_mov_b32_e32 v120, v0
	v_mov_b32_e32 v121, v0
	v_mov_b32_e32 v74, v0
	v_mov_b32_e32 v75, v0
	v_mov_b32_e32 v76, v0
	v_mov_b32_e32 v77, v0
	v_mov_b32_e32 v78, v0
	v_mov_b32_e32 v79, v0
	v_mov_b32_e32 v80, v0
	v_mov_b32_e32 v81, v0
	v_mov_b32_e32 v90, v0
	v_mov_b32_e32 v91, v0
	v_mov_b32_e32 v92, v0
	v_mov_b32_e32 v93, v0
	v_mov_b32_e32 v94, v0
	v_mov_b32_e32 v95, v0
	v_mov_b32_e32 v96, v0
	v_mov_b32_e32 v97, v0
	v_mov_b32_e32 v106, v0
	v_mov_b32_e32 v107, v0
	v_mov_b32_e32 v108, v0
	v_mov_b32_e32 v109, v0
	v_mov_b32_e32 v110, v0
	v_mov_b32_e32 v111, v0
	v_mov_b32_e32 v112, v0
	v_mov_b32_e32 v113, v0
	v_mov_b32_e32 v122, v0
	v_mov_b32_e32 v123, v0
	v_mov_b32_e32 v124, v0
	v_mov_b32_e32 v125, v0
	v_mov_b32_e32 v126, v0
	v_mov_b32_e32 v127, v0
	v_mov_b32_e32 v128, v0
	v_mov_b32_e32 v129, v0
